# speedup vs baseline: 1.0021x; 1.0021x over previous
; DI u32 fkey(float f) { u32 u = __float_as_uint(f); return (u & 0x80000000u) ? ~u : (u | 0x80000000u); }
; DI void indexer_item(const Params& p, int b, int qt16, char* smem) {
;     ...
;     const float* srow = scr + (long)q * SEQ;
;     u32 u[64];
; #pragma unroll
;     for (int r = 0; r < 64; ++r) {
;       const int key = 64 * r + lane;
;       u[r] = (key <= t) ? fkey(srow[key]) : 0u;
;     }
.LBB0_324:
	v_or_b32_e32 v104, s0, v7
	v_add_u32_e32 v102, v104, v99
	s_movk_i32 s0, 0xff
	v_cmp_lt_i32_e32 vcc, s0, v102
	s_and_saveexec_b64 s[0:1], vcc
	s_xor_b64 s[90:91], exec, s[0:1]
	s_cbranch_execz .LBB0_966
	v_ashrrev_i32_e32 v105, 31, v104
	v_lshlrev_b64 v[104:105], 14, v[104:105]
	v_lshl_add_u64 v[104:105], s[96:97], 0, v[104:105]
	v_lshl_add_u64 v[106:107], v[104:105], 0, v[0:1]
	global_load_dword v3, v[106:107], off
	global_load_dword v109, v[106:107], off offset:256
	global_load_dword v5, v[106:107], off offset:512
	global_load_dword v108, v[106:107], off offset:768
	global_load_dword v141, v[106:107], off offset:1024
	global_load_dword v142, v[106:107], off offset:1280
	global_load_dword v143, v[106:107], off offset:1536
	global_load_dword v144, v[106:107], off offset:1792
	global_load_dword v145, v[106:107], off offset:2048
	global_load_dword v146, v[106:107], off offset:2304
	global_load_dword v147, v[106:107], off offset:2560
	global_load_dword v148, v[106:107], off offset:2816
	global_load_dword v149, v[106:107], off offset:3072
	global_load_dword v150, v[106:107], off offset:3328
	global_load_dword v151, v[106:107], off offset:3584
	global_load_dword v152, v[106:107], off offset:3840
	v_lshlrev_b32_e32 v246, 2, v2
	v_mov_b32_e32 v247, v1
	v_lshl_add_u64 v[246:247], v[104:105], 0, v[246:247]
	global_load_dword v153, v[246:247], off
	v_lshlrev_b32_e32 v246, 2, v4
	v_mov_b32_e32 v247, v1
	v_lshl_add_u64 v[246:247], v[104:105], 0, v[246:247]
	global_load_dword v154, v[246:247], off
	v_lshlrev_b32_e32 v246, 2, v6
	v_mov_b32_e32 v247, v1
	v_lshl_add_u64 v[246:247], v[104:105], 0, v[246:247]
	global_load_dword v155, v[246:247], off
	v_lshlrev_b32_e32 v246, 2, v8
	v_mov_b32_e32 v247, v1
	v_lshl_add_u64 v[246:247], v[104:105], 0, v[246:247]
	global_load_dword v156, v[246:247], off
	v_lshlrev_b32_e32 v246, 2, v10
	v_mov_b32_e32 v247, v1
	v_lshl_add_u64 v[246:247], v[104:105], 0, v[246:247]
	global_load_dword v157, v[246:247], off
	v_lshlrev_b32_e32 v246, 2, v12
	v_mov_b32_e32 v247, v1
	v_lshl_add_u64 v[246:247], v[104:105], 0, v[246:247]
	global_load_dword v158, v[246:247], off
	v_lshlrev_b32_e32 v246, 2, v14
	v_mov_b32_e32 v247, v1
	v_lshl_add_u64 v[246:247], v[104:105], 0, v[246:247]
	global_load_dword v159, v[246:247], off
	v_lshlrev_b32_e32 v246, 2, v16
	v_mov_b32_e32 v247, v1
	v_lshl_add_u64 v[246:247], v[104:105], 0, v[246:247]
	global_load_dword v160, v[246:247], off
	v_lshlrev_b32_e32 v246, 2, v18
	v_mov_b32_e32 v247, v1
	v_lshl_add_u64 v[246:247], v[104:105], 0, v[246:247]
	global_load_dword v161, v[246:247], off
	v_lshlrev_b32_e32 v246, 2, v20
	v_mov_b32_e32 v247, v1
	v_lshl_add_u64 v[246:247], v[104:105], 0, v[246:247]
	global_load_dword v162, v[246:247], off
	v_lshlrev_b32_e32 v246, 2, v22
	v_mov_b32_e32 v247, v1
	v_lshl_add_u64 v[246:247], v[104:105], 0, v[246:247]
	global_load_dword v163, v[246:247], off
	v_lshlrev_b32_e32 v246, 2, v24
	v_mov_b32_e32 v247, v1
	v_lshl_add_u64 v[246:247], v[104:105], 0, v[246:247]
	global_load_dword v164, v[246:247], off
	v_lshlrev_b32_e32 v246, 2, v26
	v_mov_b32_e32 v247, v1
	v_lshl_add_u64 v[246:247], v[104:105], 0, v[246:247]
	global_load_dword v165, v[246:247], off
	v_lshlrev_b32_e32 v246, 2, v28
	v_mov_b32_e32 v247, v1
	v_lshl_add_u64 v[246:247], v[104:105], 0, v[246:247]
	global_load_dword v166, v[246:247], off
	v_lshlrev_b32_e32 v246, 2, v30
	v_mov_b32_e32 v247, v1
	v_lshl_add_u64 v[246:247], v[104:105], 0, v[246:247]
	global_load_dword v167, v[246:247], off
	v_lshlrev_b32_e32 v246, 2, v32
	v_mov_b32_e32 v247, v1
	v_lshl_add_u64 v[246:247], v[104:105], 0, v[246:247]
	global_load_dword v168, v[246:247], off
	v_lshlrev_b32_e32 v246, 2, v34
	v_mov_b32_e32 v247, v1
	v_lshl_add_u64 v[246:247], v[104:105], 0, v[246:247]
	global_load_dword v169, v[246:247], off
	v_lshlrev_b32_e32 v246, 2, v36
	v_mov_b32_e32 v247, v1
	v_lshl_add_u64 v[246:247], v[104:105], 0, v[246:247]
	global_load_dword v170, v[246:247], off
	v_lshlrev_b32_e32 v246, 2, v38
	v_mov_b32_e32 v247, v1
	v_lshl_add_u64 v[246:247], v[104:105], 0, v[246:247]
	global_load_dword v171, v[246:247], off
	v_lshlrev_b32_e32 v246, 2, v40
	v_mov_b32_e32 v247, v1
	v_lshl_add_u64 v[246:247], v[104:105], 0, v[246:247]
	global_load_dword v172, v[246:247], off
	v_lshlrev_b32_e32 v246, 2, v42
	v_mov_b32_e32 v247, v1
	v_lshl_add_u64 v[246:247], v[104:105], 0, v[246:247]
	global_load_dword v173, v[246:247], off
	v_lshlrev_b32_e32 v246, 2, v44
	v_mov_b32_e32 v247, v1
	v_lshl_add_u64 v[246:247], v[104:105], 0, v[246:247]
	global_load_dword v174, v[246:247], off
	v_lshlrev_b32_e32 v246, 2, v46
	v_mov_b32_e32 v247, v1
	v_lshl_add_u64 v[246:247], v[104:105], 0, v[246:247]
	global_load_dword v175, v[246:247], off
	v_lshlrev_b32_e32 v246, 2, v48
	v_mov_b32_e32 v247, v1
	v_lshl_add_u64 v[246:247], v[104:105], 0, v[246:247]
	global_load_dword v176, v[246:247], off
	v_lshlrev_b32_e32 v246, 2, v50
	v_mov_b32_e32 v247, v1
	v_lshl_add_u64 v[246:247], v[104:105], 0, v[246:247]
	global_load_dword v177, v[246:247], off
	v_lshlrev_b32_e32 v246, 2, v52
	v_mov_b32_e32 v247, v1
	v_lshl_add_u64 v[246:247], v[104:105], 0, v[246:247]
	global_load_dword v178, v[246:247], off
	v_lshlrev_b32_e32 v246, 2, v54
	v_mov_b32_e32 v247, v1
	v_lshl_add_u64 v[246:247], v[104:105], 0, v[246:247]
	global_load_dword v179, v[246:247], off
	v_lshlrev_b32_e32 v246, 2, v56
	v_mov_b32_e32 v247, v1
	v_lshl_add_u64 v[246:247], v[104:105], 0, v[246:247]
	global_load_dword v180, v[246:247], off
	v_lshlrev_b32_e32 v246, 2, v58
	v_mov_b32_e32 v247, v1
	v_lshl_add_u64 v[246:247], v[104:105], 0, v[246:247]
	global_load_dword v181, v[246:247], off
	v_lshlrev_b32_e32 v246, 2, v60
; DI u32 fkey(float f) { u32 u = __float_as_uint(f); return (u & 0x80000000u) ? ~u : (u | 0x80000000u); }
; DI void indexer_item(const Params& p, int b, int qt16, char* smem) {
;     ...
;     const float* srow = scr + (long)q * SEQ;
;     u32 u[64];
; #pragma unroll
;     for (int r = 0; r < 64; ++r) {
;       const int key = 64 * r + lane;
;       u[r] = (key <= t) ? fkey(srow[key]) : 0u;
;     }
	v_mov_b32_e32 v247, v1
	v_lshl_add_u64 v[246:247], v[104:105], 0, v[246:247]
	global_load_dword v182, v[246:247], off
	v_lshlrev_b32_e32 v246, 2, v62
	v_mov_b32_e32 v247, v1
	v_lshl_add_u64 v[246:247], v[104:105], 0, v[246:247]
	global_load_dword v183, v[246:247], off
	v_lshlrev_b32_e32 v246, 2, v64
	v_mov_b32_e32 v247, v1
	v_lshl_add_u64 v[246:247], v[104:105], 0, v[246:247]
	global_load_dword v184, v[246:247], off
	v_lshlrev_b32_e32 v246, 2, v66
	v_mov_b32_e32 v247, v1
	v_lshl_add_u64 v[246:247], v[104:105], 0, v[246:247]
	global_load_dword v185, v[246:247], off
	v_lshlrev_b32_e32 v246, 2, v68
	v_mov_b32_e32 v247, v1
	v_lshl_add_u64 v[246:247], v[104:105], 0, v[246:247]
	global_load_dword v186, v[246:247], off
	v_lshlrev_b32_e32 v246, 2, v70
	v_mov_b32_e32 v247, v1
	v_lshl_add_u64 v[246:247], v[104:105], 0, v[246:247]
	global_load_dword v187, v[246:247], off
	v_lshlrev_b32_e32 v246, 2, v72
	v_mov_b32_e32 v247, v1
	v_lshl_add_u64 v[246:247], v[104:105], 0, v[246:247]
	global_load_dword v198, v[246:247], off
	v_lshlrev_b32_e32 v246, 2, v74
	v_mov_b32_e32 v247, v1
	v_lshl_add_u64 v[246:247], v[104:105], 0, v[246:247]
	global_load_dword v199, v[246:247], off
	v_lshlrev_b32_e32 v246, 2, v76
	v_mov_b32_e32 v247, v1
	v_lshl_add_u64 v[246:247], v[104:105], 0, v[246:247]
	global_load_dword v200, v[246:247], off
	v_lshlrev_b32_e32 v246, 2, v78
	v_mov_b32_e32 v247, v1
	v_lshl_add_u64 v[246:247], v[104:105], 0, v[246:247]
	global_load_dword v201, v[246:247], off
	v_lshlrev_b32_e32 v246, 2, v80
	v_mov_b32_e32 v247, v1
	v_lshl_add_u64 v[246:247], v[104:105], 0, v[246:247]
	global_load_dword v202, v[246:247], off
	v_lshlrev_b32_e32 v246, 2, v82
	v_mov_b32_e32 v247, v1
	v_lshl_add_u64 v[246:247], v[104:105], 0, v[246:247]
	global_load_dword v203, v[246:247], off
	v_lshlrev_b32_e32 v246, 2, v84
	v_mov_b32_e32 v247, v1
	v_lshl_add_u64 v[246:247], v[104:105], 0, v[246:247]
	global_load_dword v204, v[246:247], off
	v_lshlrev_b32_e32 v246, 2, v88
	v_mov_b32_e32 v247, v1
	v_lshl_add_u64 v[246:247], v[104:105], 0, v[246:247]
	global_load_dword v205, v[246:247], off
	v_lshlrev_b32_e32 v246, 2, v90
	v_mov_b32_e32 v247, v1
	v_lshl_add_u64 v[246:247], v[104:105], 0, v[246:247]
	global_load_dword v206, v[246:247], off
	v_cmp_le_i32_e32 vcc, v13, v102
	v_mov_b32_e32 v39, 0
	v_mov_b32_e32 v41, 0
	s_and_saveexec_b64 s[0:1], vcc
	s_cbranch_execz .LBB0_327
	s_waitcnt vmcnt(55)
	v_mov_b32_e32 v37, v141
	v_not_b32_e32 v41, v37
	v_or_b32_e32 v43, 0x80000000, v37
	v_cmp_gt_i32_e32 vcc, 0, v37
	s_nop 1
	v_cndmask_b32_e32 v41, v43, v41, vcc
.LBB0_327:
	s_or_b64 exec, exec, s[0:1]
	v_cmp_le_i32_e32 vcc, v15, v102
	s_and_saveexec_b64 s[0:1], vcc
	s_cbranch_execz .LBB0_329
	s_waitcnt vmcnt(54)
	v_mov_b32_e32 v37, v142
	v_not_b32_e32 v39, v37
	v_or_b32_e32 v43, 0x80000000, v37
	v_cmp_gt_i32_e32 vcc, 0, v37
	s_nop 1
	v_cndmask_b32_e32 v39, v43, v39, vcc
.LBB0_329:
	s_or_b64 exec, exec, s[0:1]
	v_cmp_le_i32_e32 vcc, v17, v102
	v_mov_b32_e32 v37, 0
	v_mov_b32_e32 v47, 0
	s_and_saveexec_b64 s[0:1], vcc
	s_cbranch_execz .LBB0_331
	s_waitcnt vmcnt(53)
	v_mov_b32_e32 v43, v143
	v_not_b32_e32 v45, v43
	v_or_b32_e32 v47, 0x80000000, v43
	v_cmp_gt_i32_e32 vcc, 0, v43
	s_nop 1
	v_cndmask_b32_e32 v47, v47, v45, vcc
.LBB0_331:
	s_or_b64 exec, exec, s[0:1]
	v_cmp_le_i32_e32 vcc, v19, v102
	s_and_saveexec_b64 s[0:1], vcc
	s_cbranch_execz .LBB0_333
	s_waitcnt vmcnt(52)
	v_mov_b32_e32 v37, v144
	v_not_b32_e32 v43, v37
	v_or_b32_e32 v45, 0x80000000, v37
	v_cmp_gt_i32_e32 vcc, 0, v37
	s_nop 1
	v_cndmask_b32_e32 v37, v45, v43, vcc
.LBB0_333:
	s_or_b64 exec, exec, s[0:1]
	v_cmp_le_i32_e32 vcc, v21, v102
	v_mov_b32_e32 v43, 0
	v_mov_b32_e32 v45, 0
	s_and_saveexec_b64 s[0:1], vcc
	s_cbranch_execz .LBB0_335
	s_waitcnt vmcnt(51)
	v_mov_b32_e32 v45, v145
	v_not_b32_e32 v49, v45
	v_or_b32_e32 v51, 0x80000000, v45
	v_cmp_gt_i32_e32 vcc, 0, v45
	s_nop 1
	v_cndmask_b32_e32 v45, v51, v49, vcc
.LBB0_335:
	s_or_b64 exec, exec, s[0:1]
	v_cmp_le_i32_e32 vcc, v23, v102
	s_and_saveexec_b64 s[0:1], vcc
	s_cbranch_execz .LBB0_337
	s_waitcnt vmcnt(50)
	v_mov_b32_e32 v43, v146
	v_not_b32_e32 v49, v43
	v_or_b32_e32 v51, 0x80000000, v43
	v_cmp_gt_i32_e32 vcc, 0, v43
	s_nop 1
	v_cndmask_b32_e32 v43, v51, v49, vcc
.LBB0_337:
	s_or_b64 exec, exec, s[0:1]
	v_cmp_le_i32_e32 vcc, v25, v102
	v_mov_b32_e32 v49, 0
	v_mov_b32_e32 v51, 0
	s_and_saveexec_b64 s[0:1], vcc
	s_cbranch_execz .LBB0_339
	s_waitcnt vmcnt(49)
	v_mov_b32_e32 v51, v147
	v_not_b32_e32 v53, v51
	v_or_b32_e32 v55, 0x80000000, v51
	v_cmp_gt_i32_e32 vcc, 0, v51
	s_nop 1
	v_cndmask_b32_e32 v51, v55, v53, vcc
.LBB0_339:
	s_or_b64 exec, exec, s[0:1]
	v_cmp_le_i32_e32 vcc, v27, v102
	s_and_saveexec_b64 s[0:1], vcc
	s_cbranch_execz .LBB0_341
	s_waitcnt vmcnt(48)
	v_mov_b32_e32 v49, v148
	v_not_b32_e32 v53, v49
	v_or_b32_e32 v55, 0x80000000, v49
	v_cmp_gt_i32_e32 vcc, 0, v49
	s_nop 1
	v_cndmask_b32_e32 v49, v55, v53, vcc
.LBB0_341:
	s_or_b64 exec, exec, s[0:1]
	v_cmp_le_i32_e32 vcc, v29, v102
	v_mov_b32_e32 v55, 0
	v_mov_b32_e32 v57, 0
	s_and_saveexec_b64 s[0:1], vcc
	s_cbranch_execz .LBB0_343
	s_waitcnt vmcnt(47)
	v_mov_b32_e32 v53, v149
	v_not_b32_e32 v57, v53
	v_or_b32_e32 v59, 0x80000000, v53
	v_cmp_gt_i32_e32 vcc, 0, v53
	s_nop 1
	v_cndmask_b32_e32 v57, v59, v57, vcc
.LBB0_343:
	s_or_b64 exec, exec, s[0:1]
	v_cmp_le_i32_e32 vcc, v31, v102
	s_and_saveexec_b64 s[0:1], vcc
	s_cbranch_execz .LBB0_345
	s_waitcnt vmcnt(46)
	v_mov_b32_e32 v53, v150
	v_not_b32_e32 v55, v53
	v_or_b32_e32 v59, 0x80000000, v53
	v_cmp_gt_i32_e32 vcc, 0, v53
	s_nop 1
	v_cndmask_b32_e32 v55, v59, v55, vcc
; DI u32 fkey(float f) { u32 u = __float_as_uint(f); return (u & 0x80000000u) ? ~u : (u | 0x80000000u); }
; DI void indexer_item(const Params& p, int b, int qt16, char* smem) {
;     ...
;     const float* srow = scr + (long)q * SEQ;
;     u32 u[64];
; #pragma unroll
;     for (int r = 0; r < 64; ++r) {
;       const int key = 64 * r + lane;
;       u[r] = (key <= t) ? fkey(srow[key]) : 0u;
;     }
.LBB0_345:
	s_or_b64 exec, exec, s[0:1]
	v_cmp_le_i32_e32 vcc, v33, v102
	v_mov_b32_e32 v53, 0
	v_mov_b32_e32 v63, 0
	s_and_saveexec_b64 s[0:1], vcc
	s_cbranch_execz .LBB0_347
	s_waitcnt vmcnt(45)
	v_mov_b32_e32 v59, v151
	v_not_b32_e32 v61, v59
	v_or_b32_e32 v63, 0x80000000, v59
	v_cmp_gt_i32_e32 vcc, 0, v59
	s_nop 1
	v_cndmask_b32_e32 v63, v63, v61, vcc
.LBB0_347:
	s_or_b64 exec, exec, s[0:1]
	v_cmp_le_i32_e32 vcc, v35, v102
	s_and_saveexec_b64 s[0:1], vcc
	s_cbranch_execz .LBB0_349
	s_waitcnt vmcnt(44)
	v_mov_b32_e32 v53, v152
	v_not_b32_e32 v59, v53
	v_or_b32_e32 v61, 0x80000000, v53
	v_cmp_gt_i32_e32 vcc, 0, v53
	s_nop 1
	v_cndmask_b32_e32 v53, v61, v59, vcc
.LBB0_349:
	s_or_b64 exec, exec, s[0:1]
	v_cmp_le_i32_e32 vcc, v2, v102
	v_mov_b32_e32 v59, 0
	v_mov_b32_e32 v61, 0
	s_and_saveexec_b64 s[0:1], vcc
	s_cbranch_execz .LBB0_351
	v_lshlrev_b32_e32 v106, 2, v2
	v_mov_b32_e32 v107, v1
	v_lshl_add_u64 v[106:107], v[104:105], 0, v[106:107]
	s_waitcnt vmcnt(43)
	v_mov_b32_e32 v61, v153
	v_not_b32_e32 v65, v61
	v_or_b32_e32 v67, 0x80000000, v61
	v_cmp_gt_i32_e32 vcc, 0, v61
	s_nop 1
	v_cndmask_b32_e32 v61, v67, v65, vcc
.LBB0_351:
	s_or_b64 exec, exec, s[0:1]
	v_cmp_le_i32_e32 vcc, v4, v102
	s_and_saveexec_b64 s[0:1], vcc
	s_cbranch_execz .LBB0_353
	v_lshlrev_b32_e32 v106, 2, v4
	v_mov_b32_e32 v107, v1
	v_lshl_add_u64 v[106:107], v[104:105], 0, v[106:107]
	s_waitcnt vmcnt(42)
	v_mov_b32_e32 v59, v154
	v_not_b32_e32 v65, v59
	v_or_b32_e32 v67, 0x80000000, v59
	v_cmp_gt_i32_e32 vcc, 0, v59
	s_nop 1
	v_cndmask_b32_e32 v59, v67, v65, vcc
.LBB0_353:
	s_or_b64 exec, exec, s[0:1]
	v_cmp_le_i32_e32 vcc, v6, v102
	v_mov_b32_e32 v65, 0
	v_mov_b32_e32 v67, 0
	s_and_saveexec_b64 s[0:1], vcc
	s_cbranch_execz .LBB0_355
	v_lshlrev_b32_e32 v106, 2, v6
	v_mov_b32_e32 v107, v1
	v_lshl_add_u64 v[106:107], v[104:105], 0, v[106:107]
	s_waitcnt vmcnt(41)
	v_mov_b32_e32 v67, v155
	v_not_b32_e32 v69, v67
	v_or_b32_e32 v71, 0x80000000, v67
	v_cmp_gt_i32_e32 vcc, 0, v67
	s_nop 1
	v_cndmask_b32_e32 v67, v71, v69, vcc
.LBB0_355:
	s_or_b64 exec, exec, s[0:1]
	v_cmp_le_i32_e32 vcc, v8, v102
	s_and_saveexec_b64 s[0:1], vcc
	s_cbranch_execz .LBB0_357
	v_lshlrev_b32_e32 v106, 2, v8
	v_mov_b32_e32 v107, v1
	v_lshl_add_u64 v[106:107], v[104:105], 0, v[106:107]
	s_waitcnt vmcnt(40)
	v_mov_b32_e32 v65, v156
	v_not_b32_e32 v69, v65
	v_or_b32_e32 v71, 0x80000000, v65
	v_cmp_gt_i32_e32 vcc, 0, v65
	s_nop 1
	v_cndmask_b32_e32 v65, v71, v69, vcc
.LBB0_357:
	s_or_b64 exec, exec, s[0:1]
	v_cmp_le_i32_e32 vcc, v10, v102
	v_mov_b32_e32 v71, 0
	v_mov_b32_e32 v73, 0
	s_and_saveexec_b64 s[0:1], vcc
	s_cbranch_execz .LBB0_359
	v_lshlrev_b32_e32 v106, 2, v10
	v_mov_b32_e32 v107, v1
	v_lshl_add_u64 v[106:107], v[104:105], 0, v[106:107]
	s_waitcnt vmcnt(39)
	v_mov_b32_e32 v69, v157
	v_not_b32_e32 v73, v69
	v_or_b32_e32 v75, 0x80000000, v69
	v_cmp_gt_i32_e32 vcc, 0, v69
	s_nop 1
	v_cndmask_b32_e32 v73, v75, v73, vcc
.LBB0_359:
	s_or_b64 exec, exec, s[0:1]
	v_cmp_le_i32_e32 vcc, v12, v102
	s_and_saveexec_b64 s[0:1], vcc
	s_cbranch_execz .LBB0_361
	v_lshlrev_b32_e32 v106, 2, v12
	v_mov_b32_e32 v107, v1
	v_lshl_add_u64 v[106:107], v[104:105], 0, v[106:107]
	s_waitcnt vmcnt(38)
	v_mov_b32_e32 v69, v158
	v_not_b32_e32 v71, v69
	v_or_b32_e32 v75, 0x80000000, v69
	v_cmp_gt_i32_e32 vcc, 0, v69
	s_nop 1
	v_cndmask_b32_e32 v71, v75, v71, vcc
.LBB0_361:
	s_or_b64 exec, exec, s[0:1]
	v_cmp_le_i32_e32 vcc, v14, v102
	v_mov_b32_e32 v69, 0
	v_mov_b32_e32 v79, 0
	s_and_saveexec_b64 s[0:1], vcc
	s_cbranch_execz .LBB0_363
	v_lshlrev_b32_e32 v106, 2, v14
	v_mov_b32_e32 v107, v1
	v_lshl_add_u64 v[106:107], v[104:105], 0, v[106:107]
	s_waitcnt vmcnt(37)
	v_mov_b32_e32 v75, v159
	v_not_b32_e32 v77, v75
	v_or_b32_e32 v79, 0x80000000, v75
	v_cmp_gt_i32_e32 vcc, 0, v75
	s_nop 1
	v_cndmask_b32_e32 v79, v79, v77, vcc
.LBB0_363:
	s_or_b64 exec, exec, s[0:1]
	v_cmp_le_i32_e32 vcc, v16, v102
	s_and_saveexec_b64 s[0:1], vcc
	s_cbranch_execz .LBB0_365
	v_lshlrev_b32_e32 v106, 2, v16
	v_mov_b32_e32 v107, v1
	v_lshl_add_u64 v[106:107], v[104:105], 0, v[106:107]
	s_waitcnt vmcnt(36)
	v_mov_b32_e32 v69, v160
	v_not_b32_e32 v75, v69
	v_or_b32_e32 v77, 0x80000000, v69
	v_cmp_gt_i32_e32 vcc, 0, v69
	s_nop 1
	v_cndmask_b32_e32 v69, v77, v75, vcc
; DI u32 fkey(float f) { u32 u = __float_as_uint(f); return (u & 0x80000000u) ? ~u : (u | 0x80000000u); }
; DI void indexer_item(const Params& p, int b, int qt16, char* smem) {
;     ...
;     const float* srow = scr + (long)q * SEQ;
;     u32 u[64];
; #pragma unroll
;     for (int r = 0; r < 64; ++r) {
;       const int key = 64 * r + lane;
;       u[r] = (key <= t) ? fkey(srow[key]) : 0u;
;     }
.LBB0_365:
	s_or_b64 exec, exec, s[0:1]
	v_cmp_le_i32_e32 vcc, v18, v102
	v_mov_b32_e32 v75, 0
	v_mov_b32_e32 v77, 0
	s_and_saveexec_b64 s[0:1], vcc
	s_cbranch_execz .LBB0_367
	v_lshlrev_b32_e32 v106, 2, v18
	v_mov_b32_e32 v107, v1
	v_lshl_add_u64 v[106:107], v[104:105], 0, v[106:107]
	s_waitcnt vmcnt(35)
	v_mov_b32_e32 v77, v161
	v_not_b32_e32 v81, v77
	v_or_b32_e32 v83, 0x80000000, v77
	v_cmp_gt_i32_e32 vcc, 0, v77
	s_nop 1
	v_cndmask_b32_e32 v77, v83, v81, vcc
.LBB0_367:
	s_or_b64 exec, exec, s[0:1]
	v_cmp_le_i32_e32 vcc, v20, v102
	s_and_saveexec_b64 s[0:1], vcc
	s_cbranch_execz .LBB0_369
	v_lshlrev_b32_e32 v106, 2, v20
	v_mov_b32_e32 v107, v1
	v_lshl_add_u64 v[106:107], v[104:105], 0, v[106:107]
	s_waitcnt vmcnt(34)
	v_mov_b32_e32 v75, v162
	v_not_b32_e32 v81, v75
	v_or_b32_e32 v83, 0x80000000, v75
	v_cmp_gt_i32_e32 vcc, 0, v75
	s_nop 1
	v_cndmask_b32_e32 v75, v83, v81, vcc
.LBB0_369:
	s_or_b64 exec, exec, s[0:1]
	v_cmp_le_i32_e32 vcc, v22, v102
	v_mov_b32_e32 v81, 0
	v_mov_b32_e32 v83, 0
	s_and_saveexec_b64 s[0:1], vcc
	s_cbranch_execz .LBB0_371
	v_lshlrev_b32_e32 v106, 2, v22
	v_mov_b32_e32 v107, v1
	v_lshl_add_u64 v[106:107], v[104:105], 0, v[106:107]
	s_waitcnt vmcnt(33)
	v_mov_b32_e32 v83, v163
	v_not_b32_e32 v85, v83
	v_or_b32_e32 v89, 0x80000000, v83
	v_cmp_gt_i32_e32 vcc, 0, v83
	s_nop 1
	v_cndmask_b32_e32 v83, v89, v85, vcc
.LBB0_371:
	s_or_b64 exec, exec, s[0:1]
	v_cmp_le_i32_e32 vcc, v24, v102
	s_and_saveexec_b64 s[0:1], vcc
	s_cbranch_execz .LBB0_373
	v_lshlrev_b32_e32 v106, 2, v24
	v_mov_b32_e32 v107, v1
	v_lshl_add_u64 v[106:107], v[104:105], 0, v[106:107]
	s_waitcnt vmcnt(32)
	v_mov_b32_e32 v81, v164
	v_not_b32_e32 v85, v81
	v_or_b32_e32 v89, 0x80000000, v81
	v_cmp_gt_i32_e32 vcc, 0, v81
	s_nop 1
	v_cndmask_b32_e32 v81, v89, v85, vcc
.LBB0_373:
	s_or_b64 exec, exec, s[0:1]
	v_cmp_le_i32_e32 vcc, v26, v102
	v_mov_b32_e32 v89, 0
	v_mov_b32_e32 v91, 0
	s_and_saveexec_b64 s[0:1], vcc
	s_cbranch_execz .LBB0_375
	v_lshlrev_b32_e32 v106, 2, v26
	v_mov_b32_e32 v107, v1
	v_lshl_add_u64 v[106:107], v[104:105], 0, v[106:107]
	s_waitcnt vmcnt(31)
	v_mov_b32_e32 v85, v165
	v_not_b32_e32 v91, v85
	v_or_b32_e32 v93, 0x80000000, v85
	v_cmp_gt_i32_e32 vcc, 0, v85
	s_nop 1
	v_cndmask_b32_e32 v91, v93, v91, vcc
.LBB0_375:
	s_or_b64 exec, exec, s[0:1]
	v_cmp_le_i32_e32 vcc, v28, v102
	s_and_saveexec_b64 s[0:1], vcc
	s_cbranch_execz .LBB0_377
	v_lshlrev_b32_e32 v106, 2, v28
	v_mov_b32_e32 v107, v1
	v_lshl_add_u64 v[106:107], v[104:105], 0, v[106:107]
	s_waitcnt vmcnt(30)
	v_mov_b32_e32 v85, v166
	v_not_b32_e32 v89, v85
	v_or_b32_e32 v93, 0x80000000, v85
	v_cmp_gt_i32_e32 vcc, 0, v85
	s_nop 1
	v_cndmask_b32_e32 v89, v93, v89, vcc
.LBB0_377:
	s_or_b64 exec, exec, s[0:1]
	v_cmp_le_i32_e32 vcc, v30, v102
	v_mov_b32_e32 v85, 0
	v_mov_b32_e32 v97, 0
	s_and_saveexec_b64 s[0:1], vcc
	s_cbranch_execz .LBB0_379
	v_lshlrev_b32_e32 v106, 2, v30
	v_mov_b32_e32 v107, v1
	v_lshl_add_u64 v[106:107], v[104:105], 0, v[106:107]
	s_waitcnt vmcnt(29)
	v_mov_b32_e32 v93, v167
	v_not_b32_e32 v95, v93
	v_or_b32_e32 v97, 0x80000000, v93
	v_cmp_gt_i32_e32 vcc, 0, v93
	s_nop 1
	v_cndmask_b32_e32 v97, v97, v95, vcc
.LBB0_379:
	s_or_b64 exec, exec, s[0:1]
	v_cmp_le_i32_e32 vcc, v32, v102
	s_and_saveexec_b64 s[0:1], vcc
	s_cbranch_execz .LBB0_381
	v_lshlrev_b32_e32 v106, 2, v32
	v_mov_b32_e32 v107, v1
	v_lshl_add_u64 v[106:107], v[104:105], 0, v[106:107]
	s_waitcnt vmcnt(28)
	v_mov_b32_e32 v85, v168
	v_not_b32_e32 v93, v85
	v_or_b32_e32 v95, 0x80000000, v85
	v_cmp_gt_i32_e32 vcc, 0, v85
	s_nop 1
	v_cndmask_b32_e32 v85, v95, v93, vcc
.LBB0_381:
	s_or_b64 exec, exec, s[0:1]
	s_waitcnt vmcnt(28)
	v_lshlrev_b32_e32 v246, 2, v92
	v_mov_b32_e32 v247, v1
	v_lshl_add_u64 v[246:247], v[104:105], 0, v[246:247]
	global_load_dword v207, v[246:247], off
	v_lshlrev_b32_e32 v246, 2, v94
	v_mov_b32_e32 v247, v1
	v_lshl_add_u64 v[246:247], v[104:105], 0, v[246:247]
	global_load_dword v210, v[246:247], off
	v_lshlrev_b32_e32 v246, 2, v96
	v_mov_b32_e32 v247, v1
	v_lshl_add_u64 v[246:247], v[104:105], 0, v[246:247]
	global_load_dword v211, v[246:247], off
	v_lshlrev_b32_e32 v246, 2, v98
	v_mov_b32_e32 v247, v1
	v_lshl_add_u64 v[246:247], v[104:105], 0, v[246:247]
	global_load_dword v212, v[246:247], off
	v_cmp_le_i32_e32 vcc, v34, v102
	v_mov_b32_e32 v93, 0
	v_mov_b32_e32 v95, 0
	s_and_saveexec_b64 s[0:1], vcc
	s_cbranch_execz .LBB0_383
	v_lshlrev_b32_e32 v106, 2, v34
	v_mov_b32_e32 v107, v1
	v_lshl_add_u64 v[106:107], v[104:105], 0, v[106:107]
	s_waitcnt vmcnt(31)
	v_mov_b32_e32 v95, v169
	v_not_b32_e32 v103, v95
	v_or_b32_e32 v106, 0x80000000, v95
	v_cmp_gt_i32_e32 vcc, 0, v95
	s_nop 1
	v_cndmask_b32_e32 v95, v106, v103, vcc
